# fused-norm epilogues: no L1 invalidate after the row-stat exchange poll (the only cross-workgroup data read afterwards are the sc1 slot loads)
# speedup vs baseline: 1.0042x; 1.0042x over previous
.LBB0_257:
	s_waitcnt lgkmcnt(0)
.LBB0_258:
	s_waitcnt vmcnt(0) lgkmcnt(0)
	s_barrier
	v_lshl_add_u32 v223, v214, 2, 0
	s_and_saveexec_b64 s[4:5], s[40:41]
	s_cbranch_execz .LBB0_260
	global_load_dword v214, v[210:211], off sc1
	global_load_dword v215, v[210:211], off offset:4 sc1
	s_waitcnt vmcnt(0)
	v_add_f32_e32 v214, 0, v214
	v_add_f32_e32 v214, v214, v215
	global_load_dword v215, v[210:211], off offset:8 sc1
	s_waitcnt vmcnt(0)
	v_add_f32_e32 v214, v214, v215
	global_load_dword v215, v[210:211], off offset:12 sc1
	s_waitcnt vmcnt(0)
	v_add_f32_e32 v214, v214, v215
	v_fmamk_f32 v214, v214, 0x3a800000, v238
	v_rsq_f32_e32 v214, v214
	ds_write_b32 v223, v214 offset:4096

.LBB0_290:
.LBB0_291:
	s_waitcnt vmcnt(0) lgkmcnt(0)
	s_barrier
	s_and_saveexec_b64 s[4:5], s[40:41]
	s_cbranch_execz .LBB0_293
	global_load_dword v136, v[136:137], off sc1
	s_waitcnt vmcnt(0)
	v_add_f32_e32 v138, 0, v136
	v_add_co_u32_e32 v136, vcc, 0x40000, v210
	s_nop 1
	v_addc_co_u32_e32 v137, vcc, 0, v211, vcc
	global_load_dword v139, v[136:137], off offset:4 sc1
	s_waitcnt vmcnt(0)
	v_add_f32_e32 v138, v138, v139
	global_load_dword v139, v[136:137], off offset:8 sc1
	s_waitcnt vmcnt(0)
	v_add_f32_e32 v138, v138, v139
	global_load_dword v136, v[136:137], off offset:12 sc1
	s_waitcnt vmcnt(0)
	v_add_f32_e32 v136, v138, v136
	v_fmamk_f32 v136, v136, 0x3a800000, v238
	v_rsq_f32_e32 v136, v136
	ds_write_b32 v223, v136 offset:4096

.LBB0_839:
	s_waitcnt lgkmcnt(0)
.LBB0_840:
	s_waitcnt vmcnt(0) lgkmcnt(0)
	s_barrier
	v_lshl_add_u32 v223, v216, 2, 0
	s_and_saveexec_b64 s[4:5], s[40:41]
	s_cbranch_execz .LBB0_842
	global_load_dword v216, v[210:211], off sc1
	global_load_dword v217, v[210:211], off offset:4 sc1
	s_waitcnt vmcnt(0)
	v_add_f32_e32 v216, 0, v216
	v_add_f32_e32 v216, v216, v217
	global_load_dword v217, v[210:211], off offset:8 sc1
	s_waitcnt vmcnt(0)
	v_add_f32_e32 v216, v216, v217
	global_load_dword v217, v[210:211], off offset:12 sc1
	s_waitcnt vmcnt(0)
	v_add_f32_e32 v216, v216, v217
	v_fmamk_f32 v216, v216, 0x3a800000, v238
	v_rsq_f32_e32 v216, v216
	ds_write_b32 v223, v216 offset:4096

.LBB0_1074:
	s_waitcnt lgkmcnt(0)
.LBB0_1075:
	s_waitcnt vmcnt(0) lgkmcnt(0)
	s_barrier
	s_and_saveexec_b64 s[4:5], s[42:43]
	s_cbranch_execz .LBB0_1077
	global_load_dword v216, v[210:211], off sc1
	global_load_dword v217, v[210:211], off offset:4 sc1
	s_waitcnt vmcnt(0)
	v_add_f32_e32 v216, 0, v216
	v_add_f32_e32 v216, v216, v217
	global_load_dword v217, v[210:211], off offset:8 sc1
	s_waitcnt vmcnt(0)
	v_add_f32_e32 v216, v216, v217
	global_load_dword v217, v[210:211], off offset:12 sc1
	s_waitcnt vmcnt(0)
	v_add_f32_e32 v216, v216, v217
	v_fmamk_f32 v216, v216, 0x3a800000, v238
	v_rsq_f32_e32 v216, v216
	v_lshl_add_u32 v217, v222, 2, 0
	ds_write_b32 v217, v216 offset:4096

.LBB0_1108:
.LBB0_1109:
	s_waitcnt vmcnt(0) lgkmcnt(0)
	s_barrier
	s_and_saveexec_b64 s[4:5], s[42:43]
	s_cbranch_execz .LBB0_1111
	global_load_dword v136, v[136:137], off sc1
	s_waitcnt vmcnt(0)
	v_add_f32_e32 v138, 0, v136
	v_add_co_u32_e32 v136, vcc, 0x40000, v210
	s_nop 1
	v_addc_co_u32_e32 v137, vcc, 0, v211, vcc
	global_load_dword v139, v[136:137], off offset:4 sc1
	s_waitcnt vmcnt(0)
	v_add_f32_e32 v138, v138, v139
	global_load_dword v139, v[136:137], off offset:8 sc1
	s_waitcnt vmcnt(0)
	v_add_f32_e32 v138, v138, v139
	global_load_dword v136, v[136:137], off offset:12 sc1
	v_lshl_add_u32 v137, v222, 2, 0
	s_waitcnt vmcnt(0)
	v_add_f32_e32 v136, v138, v136
	v_fmamk_f32 v136, v136, 0x3a800000, v238
	v_rsq_f32_e32 v136, v136
	ds_write_b32 v137, v136 offset:4096
